# v18 + DSA indexer keys: tiled copy (1 KiB per MFMA operand tile) written by the even in-proj epilogue into the dead adaLN-partials area, scoring loop reads it (8 lines per load instead of 32)
# speedup vs baseline: 1.0544x; 1.0229x over previous
; DI bf16_t f2bf(float a) { return (bf16_t)(pk2(a, 0.f) & 0xffffu); }
; DI u32x2 pk4(float a, float b, float c, float d) { u32x2 r; r.x = pk2(a, b); r.y = pk2(c, d); return r; }
; template <class AF, class EF>
; DI void gemm_run(unsigned char* lds, int wv, const AF& af, const bf16_t* __restrict__ Bt, int ldb, int M, int N, int K, const EF& ef, int blk_off) {
;     ...
;         for (int k = 0; k < 4; ++k) {
;           auto r = __builtin_amdgcn_permlane16_swap(__float_as_uint(acc[2 * ip][j][k]), __float_as_uint(acc[2 * ip + 1][j][k]), false, false);
;           lo[k] = __uint_as_float(r[0]); hi[k] = __uint_as_float(r[1]);
;         }
;         int n = n0 + wn * 64 + (2 * ip + (q4 & 1)) * 16 + (q4 >> 1) * 8;
;         int m = m0 + wm * 128 + j * 16 + l15;
;         if (n < N) ef.store8(m, n, lo[0], lo[1], lo[2], lo[3], hi[0], hi[1], hi[2], hi[3]);
;   DI void store(int m, int n, float a, float b, float c, float d) const {
;     int bb = m >> 13, s = m & (SEQ - 1);
;     if (n >= C_VS && n < C_KW) { int e = n - C_VS; bf16_t* p = vsT + ((size_t)(bb * 128 + e)) * SEQ + s; p[0] = f2bf(a); p[SEQ] = f2bf(b); p[2 * SEQ] = f2bf(c); p[3 * SEQ] = f2bf(d); }
;     else if (n >= C_VW && n < C_GATE) { int e = n - C_VW; bf16_t* p = vwT + ((size_t)(bb * 128 + e)) * SEQ + s; p[0] = f2bf(a); p[SEQ] = f2bf(b); p[2 * SEQ] = f2bf(c); p[3 * SEQ] = f2bf(d); }
;     else *(u32x2*)(proj + (size_t)m * EIN + n) = pk4(a, b, c, d); }
.LBB0_271:
	v_readlane_b32 s20, v255, 24
	v_readlane_b32 s21, v255, 25
	v_cvt_pk_bf16_f32 v158, v126, v127
	v_cvt_pk_bf16_f32 v159, v128, v129
	v_mov_b64_e32 v[180:181], s[20:21]
	v_mad_i64_i32 v[180:181], s[20:21], v153, s87, v[180:181]
	v_cvt_pk_bf16_f32 v160, v122, v123
	v_cvt_pk_bf16_f32 v161, v124, v125
	v_lshl_add_u64 v[180:181], v[130:131], 1, v[180:181]
	flat_store_dwordx4 v[180:181], v[158:161]
	v_subrev_u32_e32 v230, 0x998, v130
	v_cmp_gt_u32_e64 s[30:31], 64, v230
	s_and_saveexec_b64 s[36:37], s[30:31]
	v_readlane_b32 s80, v255, 24
	v_readlane_b32 s81, v255, 25
	v_lshrrev_b32_e32 v231, 5, v153
	v_lshlrev_b32_e32 v231, 11, v231
	v_and_b32_e32 v232, 31, v153
	v_lshl_or_b32 v231, v232, 4, v231
	v_lshrrev_b32_e32 v232, 4, v230
	v_lshl_or_b32 v231, v232, 9, v231
	v_and_b32_e32 v232, 15, v230
	v_or_b32_e32 v231, v231, v232
	v_add_u32_e32 v234, 0x9000000, v231
	v_mov_b32_e32 v235, 0
	v_lshl_add_u64 v[236:237], v[234:235], 1, s[80:81]
	flat_store_dwordx4 v[236:237], v[158:161]
	s_or_b64 exec, exec, s[36:37]
	s_andn2_b64 s[18:19], s[18:19], exec
	s_or_b64 exec, exec, s[6:7]
	s_and_b64 exec, exec, s[18:19]
	s_cbranch_execz .LBB0_287

; DI bf16_t f2bf(float a) { return (bf16_t)(pk2(a, 0.f) & 0xffffu); }
; DI u32x2 pk4(float a, float b, float c, float d) { u32x2 r; r.x = pk2(a, b); r.y = pk2(c, d); return r; }
; template <class AF, class EF>
; DI void gemm_run(unsigned char* lds, int wv, const AF& af, const bf16_t* __restrict__ Bt, int ldb, int M, int N, int K, const EF& ef, int blk_off) {
;     ...
;         for (int k = 0; k < 4; ++k) {
;           auto r = __builtin_amdgcn_permlane16_swap(__float_as_uint(acc[2 * ip][j][k]), __float_as_uint(acc[2 * ip + 1][j][k]), false, false);
;           lo[k] = __uint_as_float(r[0]); hi[k] = __uint_as_float(r[1]);
;         }
;         int n = n0 + wn * 64 + (2 * ip + (q4 & 1)) * 16 + (q4 >> 1) * 8;
;         int m = m0 + wm * 128 + j * 16 + l15;
;         if (n < N) ef.store8(m, n, lo[0], lo[1], lo[2], lo[3], hi[0], hi[1], hi[2], hi[3]);
;   DI void store(int m, int n, float a, float b, float c, float d) const {
;     int bb = m >> 13, s = m & (SEQ - 1);
;     if (n >= C_VS && n < C_KW) { int e = n - C_VS; bf16_t* p = vsT + ((size_t)(bb * 128 + e)) * SEQ + s; p[0] = f2bf(a); p[SEQ] = f2bf(b); p[2 * SEQ] = f2bf(c); p[3 * SEQ] = f2bf(d); }
;     else if (n >= C_VW && n < C_GATE) { int e = n - C_VW; bf16_t* p = vwT + ((size_t)(bb * 128 + e)) * SEQ + s; p[0] = f2bf(a); p[SEQ] = f2bf(b); p[2 * SEQ] = f2bf(c); p[3 * SEQ] = f2bf(d); }
;     else *(u32x2*)(proj + (size_t)m * EIN + n) = pk4(a, b, c, d); }
.LBB0_287:
	s_or_b64 exec, exec, s[16:17]
	v_permlane16_swap_b32_e32 v118, v114
	v_permlane16_swap_b32_e32 v119, v115
	v_permlane16_swap_b32_e32 v120, v116
	v_permlane16_swap_b32_e32 v121, v117
	s_and_saveexec_b64 s[16:17], s[4:5]
	s_cbranch_execz .LBB0_310
	v_cmp_lt_i32_e32 vcc, s69, v152
	s_mov_b64 s[20:21], 0
	s_mov_b64 s[18:19], 0
	s_and_saveexec_b64 s[6:7], vcc
	s_xor_b64 s[6:7], exec, s[6:7]
	v_cmp_ne_u32_e32 vcc, s70, v152
	s_and_b64 s[20:21], vcc, exec
	s_mov_b64 s[18:19], exec
	s_andn2_saveexec_b64 s[22:23], s[6:7]
	v_cmp_eq_u32_e32 vcc, s71, v152
	v_cmp_ne_u32_e64 s[6:7], s71, v152
	s_andn2_b64 s[18:19], s[18:19], exec
	s_and_b64 s[26:27], vcc, exec
	s_andn2_b64 s[20:21], s[20:21], exec
	s_and_b64 s[6:7], s[6:7], exec
	s_or_b64 s[18:19], s[18:19], s[26:27]
	s_or_b64 s[20:21], s[20:21], s[6:7]
	s_or_b64 exec, exec, s[22:23]
	v_or_b32_e32 v122, 16, v153
	s_and_saveexec_b64 s[6:7], s[20:21]
	s_xor_b64 s[6:7], exec, s[6:7]
	s_cbranch_execz .LBB0_294
	v_readlane_b32 s20, v255, 24
	v_readlane_b32 s21, v255, 25
	v_cvt_pk_bf16_f32 v124, v118, v119
	v_cvt_pk_bf16_f32 v125, v120, v121
	v_mov_b64_e32 v[128:129], s[20:21]
	v_mad_i64_i32 v[128:129], s[20:21], v122, s87, v[128:129]
	v_cvt_pk_bf16_f32 v126, v114, v115
	v_cvt_pk_bf16_f32 v127, v116, v117
	v_lshl_add_u64 v[128:129], v[130:131], 1, v[128:129]
	s_andn2_b64 s[18:19], s[18:19], exec
	flat_store_dwordx4 v[128:129], v[124:127]
	v_subrev_u32_e32 v230, 0x998, v130
	v_cmp_gt_u32_e64 s[30:31], 64, v230
	s_and_saveexec_b64 s[36:37], s[30:31]
	v_readlane_b32 s80, v255, 24
	v_readlane_b32 s81, v255, 25
	v_lshrrev_b32_e32 v231, 5, v122
	v_lshlrev_b32_e32 v231, 11, v231
	v_and_b32_e32 v232, 31, v122
	v_lshl_or_b32 v231, v232, 4, v231
	v_lshrrev_b32_e32 v232, 4, v230
	v_lshl_or_b32 v231, v232, 9, v231
	v_and_b32_e32 v232, 15, v230
	v_or_b32_e32 v231, v231, v232
	v_add_u32_e32 v234, 0x9000000, v231
	v_mov_b32_e32 v235, 0
	v_lshl_add_u64 v[236:237], v[234:235], 1, s[80:81]
	flat_store_dwordx4 v[236:237], v[124:127]
	s_or_b64 exec, exec, s[36:37]

; DI bf16_t f2bf(float a) { return (bf16_t)(pk2(a, 0.f) & 0xffffu); }
; DI u32x2 pk4(float a, float b, float c, float d) { u32x2 r; r.x = pk2(a, b); r.y = pk2(c, d); return r; }
; template <class AF, class EF>
; DI void gemm_run(unsigned char* lds, int wv, const AF& af, const bf16_t* __restrict__ Bt, int ldb, int M, int N, int K, const EF& ef, int blk_off) {
;     ...
;         for (int k = 0; k < 4; ++k) {
;           auto r = __builtin_amdgcn_permlane16_swap(__float_as_uint(acc[2 * ip][j][k]), __float_as_uint(acc[2 * ip + 1][j][k]), false, false);
;           lo[k] = __uint_as_float(r[0]); hi[k] = __uint_as_float(r[1]);
;         }
;         int n = n0 + wn * 64 + (2 * ip + (q4 & 1)) * 16 + (q4 >> 1) * 8;
;         int m = m0 + wm * 128 + j * 16 + l15;
;         if (n < N) ef.store8(m, n, lo[0], lo[1], lo[2], lo[3], hi[0], hi[1], hi[2], hi[3]);
;   DI void store(int m, int n, float a, float b, float c, float d) const {
;     int bb = m >> 13, s = m & (SEQ - 1);
;     if (n >= C_VS && n < C_KW) { int e = n - C_VS; bf16_t* p = vsT + ((size_t)(bb * 128 + e)) * SEQ + s; p[0] = f2bf(a); p[SEQ] = f2bf(b); p[2 * SEQ] = f2bf(c); p[3 * SEQ] = f2bf(d); }
;     else if (n >= C_VW && n < C_GATE) { int e = n - C_VW; bf16_t* p = vwT + ((size_t)(bb * 128 + e)) * SEQ + s; p[0] = f2bf(a); p[SEQ] = f2bf(b); p[2 * SEQ] = f2bf(c); p[3 * SEQ] = f2bf(d); }
;     else *(u32x2*)(proj + (size_t)m * EIN + n) = pk4(a, b, c, d); }
.LBB0_310:
	s_or_b64 exec, exec, s[16:17]
	v_permlane16_swap_b32_e32 v110, v106
	v_permlane16_swap_b32_e32 v111, v107
	v_permlane16_swap_b32_e32 v112, v108
	v_permlane16_swap_b32_e32 v113, v109
	s_and_saveexec_b64 s[16:17], s[4:5]
	s_cbranch_execz .LBB0_333
	v_cmp_lt_i32_e32 vcc, s69, v152
	s_mov_b64 s[20:21], 0
	s_mov_b64 s[18:19], 0
	s_and_saveexec_b64 s[6:7], vcc
	s_xor_b64 s[6:7], exec, s[6:7]
	v_cmp_ne_u32_e32 vcc, s70, v152
	s_and_b64 s[20:21], vcc, exec
	s_mov_b64 s[18:19], exec
	s_andn2_saveexec_b64 s[22:23], s[6:7]
	v_cmp_eq_u32_e32 vcc, s71, v152
	v_cmp_ne_u32_e64 s[6:7], s71, v152
	s_andn2_b64 s[18:19], s[18:19], exec
	s_and_b64 s[26:27], vcc, exec
	s_andn2_b64 s[20:21], s[20:21], exec
	s_and_b64 s[6:7], s[6:7], exec
	s_or_b64 s[18:19], s[18:19], s[26:27]
	s_or_b64 s[20:21], s[20:21], s[6:7]
	s_or_b64 exec, exec, s[22:23]
	v_or_b32_e32 v114, 32, v153
	s_and_saveexec_b64 s[6:7], s[20:21]
	s_xor_b64 s[6:7], exec, s[6:7]
	s_cbranch_execz .LBB0_317
	v_readlane_b32 s20, v255, 24
	v_readlane_b32 s21, v255, 25
	v_cvt_pk_bf16_f32 v116, v110, v111
	v_cvt_pk_bf16_f32 v117, v112, v113
	v_mov_b64_e32 v[120:121], s[20:21]
	v_mad_i64_i32 v[120:121], s[20:21], v114, s87, v[120:121]
	v_cvt_pk_bf16_f32 v118, v106, v107
	v_cvt_pk_bf16_f32 v119, v108, v109
	v_lshl_add_u64 v[120:121], v[130:131], 1, v[120:121]
	s_andn2_b64 s[18:19], s[18:19], exec
	flat_store_dwordx4 v[120:121], v[116:119]
	v_subrev_u32_e32 v230, 0x998, v130
	v_cmp_gt_u32_e64 s[30:31], 64, v230
	s_and_saveexec_b64 s[36:37], s[30:31]
	v_readlane_b32 s80, v255, 24
	v_readlane_b32 s81, v255, 25
	v_lshrrev_b32_e32 v231, 5, v114
	v_lshlrev_b32_e32 v231, 11, v231
	v_and_b32_e32 v232, 31, v114
	v_lshl_or_b32 v231, v232, 4, v231
	v_lshrrev_b32_e32 v232, 4, v230
	v_lshl_or_b32 v231, v232, 9, v231
	v_and_b32_e32 v232, 15, v230
	v_or_b32_e32 v231, v231, v232
	v_add_u32_e32 v234, 0x9000000, v231
	v_mov_b32_e32 v235, 0
	v_lshl_add_u64 v[236:237], v[234:235], 1, s[80:81]
	flat_store_dwordx4 v[236:237], v[116:119]
	s_or_b64 exec, exec, s[36:37]

; DI bf16_t f2bf(float a) { return (bf16_t)(pk2(a, 0.f) & 0xffffu); }
; DI u32x2 pk4(float a, float b, float c, float d) { u32x2 r; r.x = pk2(a, b); r.y = pk2(c, d); return r; }
; template <class AF, class EF>
; DI void gemm_run(unsigned char* lds, int wv, const AF& af, const bf16_t* __restrict__ Bt, int ldb, int M, int N, int K, const EF& ef, int blk_off) {
;     ...
;         for (int k = 0; k < 4; ++k) {
;           auto r = __builtin_amdgcn_permlane16_swap(__float_as_uint(acc[2 * ip][j][k]), __float_as_uint(acc[2 * ip + 1][j][k]), false, false);
;           lo[k] = __uint_as_float(r[0]); hi[k] = __uint_as_float(r[1]);
;         }
;         int n = n0 + wn * 64 + (2 * ip + (q4 & 1)) * 16 + (q4 >> 1) * 8;
;         int m = m0 + wm * 128 + j * 16 + l15;
;         if (n < N) ef.store8(m, n, lo[0], lo[1], lo[2], lo[3], hi[0], hi[1], hi[2], hi[3]);
;   DI void store(int m, int n, float a, float b, float c, float d) const {
;     int bb = m >> 13, s = m & (SEQ - 1);
;     if (n >= C_VS && n < C_KW) { int e = n - C_VS; bf16_t* p = vsT + ((size_t)(bb * 128 + e)) * SEQ + s; p[0] = f2bf(a); p[SEQ] = f2bf(b); p[2 * SEQ] = f2bf(c); p[3 * SEQ] = f2bf(d); }
;     else if (n >= C_VW && n < C_GATE) { int e = n - C_VW; bf16_t* p = vwT + ((size_t)(bb * 128 + e)) * SEQ + s; p[0] = f2bf(a); p[SEQ] = f2bf(b); p[2 * SEQ] = f2bf(c); p[3 * SEQ] = f2bf(d); }
;     else *(u32x2*)(proj + (size_t)m * EIN + n) = pk4(a, b, c, d); }
.LBB0_333:
	s_or_b64 exec, exec, s[16:17]
	v_permlane16_swap_b32_e32 v102, v98
	v_permlane16_swap_b32_e32 v103, v99
	v_permlane16_swap_b32_e32 v104, v100
	v_permlane16_swap_b32_e32 v105, v101
	s_and_saveexec_b64 s[16:17], s[4:5]
	s_cbranch_execz .LBB0_356
	v_cmp_lt_i32_e32 vcc, s69, v152
	s_mov_b64 s[20:21], 0
	s_mov_b64 s[18:19], 0
	s_and_saveexec_b64 s[6:7], vcc
	s_xor_b64 s[6:7], exec, s[6:7]
	v_cmp_ne_u32_e32 vcc, s70, v152
	s_and_b64 s[20:21], vcc, exec
	s_mov_b64 s[18:19], exec
	s_andn2_saveexec_b64 s[22:23], s[6:7]
	v_cmp_eq_u32_e32 vcc, s71, v152
	v_cmp_ne_u32_e64 s[6:7], s71, v152
	s_andn2_b64 s[18:19], s[18:19], exec
	s_and_b64 s[26:27], vcc, exec
	s_andn2_b64 s[20:21], s[20:21], exec
	s_and_b64 s[6:7], s[6:7], exec
	s_or_b64 s[18:19], s[18:19], s[26:27]
	s_or_b64 s[20:21], s[20:21], s[6:7]
	s_or_b64 exec, exec, s[22:23]
	v_or_b32_e32 v106, 48, v153
	s_and_saveexec_b64 s[6:7], s[20:21]
	s_xor_b64 s[6:7], exec, s[6:7]
	s_cbranch_execz .LBB0_340
	v_readlane_b32 s20, v255, 24
	v_readlane_b32 s21, v255, 25
	v_cvt_pk_bf16_f32 v108, v102, v103
	v_cvt_pk_bf16_f32 v109, v104, v105
	v_mov_b64_e32 v[112:113], s[20:21]
	v_mad_i64_i32 v[112:113], s[20:21], v106, s87, v[112:113]
	v_cvt_pk_bf16_f32 v110, v98, v99
	v_cvt_pk_bf16_f32 v111, v100, v101
	v_lshl_add_u64 v[112:113], v[130:131], 1, v[112:113]
	s_andn2_b64 s[18:19], s[18:19], exec
	flat_store_dwordx4 v[112:113], v[108:111]
	v_subrev_u32_e32 v230, 0x998, v130
	v_cmp_gt_u32_e64 s[30:31], 64, v230
	s_and_saveexec_b64 s[36:37], s[30:31]
	v_readlane_b32 s80, v255, 24
	v_readlane_b32 s81, v255, 25
	v_lshrrev_b32_e32 v231, 5, v106
	v_lshlrev_b32_e32 v231, 11, v231
	v_and_b32_e32 v232, 31, v106
	v_lshl_or_b32 v231, v232, 4, v231
	v_lshrrev_b32_e32 v232, 4, v230
	v_lshl_or_b32 v231, v232, 9, v231
	v_and_b32_e32 v232, 15, v230
	v_or_b32_e32 v231, v231, v232
	v_add_u32_e32 v234, 0x9000000, v231
	v_mov_b32_e32 v235, 0
	v_lshl_add_u64 v[236:237], v[234:235], 1, s[80:81]
	flat_store_dwordx4 v[236:237], v[108:111]
	s_or_b64 exec, exec, s[36:37]

; DI bf16_t f2bf(float a) { return (bf16_t)(pk2(a, 0.f) & 0xffffu); }
; DI u32x2 pk4(float a, float b, float c, float d) { u32x2 r; r.x = pk2(a, b); r.y = pk2(c, d); return r; }
; template <class AF, class EF>
; DI void gemm_run(unsigned char* lds, int wv, const AF& af, const bf16_t* __restrict__ Bt, int ldb, int M, int N, int K, const EF& ef, int blk_off) {
;     ...
;         for (int k = 0; k < 4; ++k) {
;           auto r = __builtin_amdgcn_permlane16_swap(__float_as_uint(acc[2 * ip][j][k]), __float_as_uint(acc[2 * ip + 1][j][k]), false, false);
;           lo[k] = __uint_as_float(r[0]); hi[k] = __uint_as_float(r[1]);
;         }
;         int n = n0 + wn * 64 + (2 * ip + (q4 & 1)) * 16 + (q4 >> 1) * 8;
;         int m = m0 + wm * 128 + j * 16 + l15;
;         if (n < N) ef.store8(m, n, lo[0], lo[1], lo[2], lo[3], hi[0], hi[1], hi[2], hi[3]);
;   DI void store(int m, int n, float a, float b, float c, float d) const {
;     int bb = m >> 13, s = m & (SEQ - 1);
;     if (n >= C_VS && n < C_KW) { int e = n - C_VS; bf16_t* p = vsT + ((size_t)(bb * 128 + e)) * SEQ + s; p[0] = f2bf(a); p[SEQ] = f2bf(b); p[2 * SEQ] = f2bf(c); p[3 * SEQ] = f2bf(d); }
;     else if (n >= C_VW && n < C_GATE) { int e = n - C_VW; bf16_t* p = vwT + ((size_t)(bb * 128 + e)) * SEQ + s; p[0] = f2bf(a); p[SEQ] = f2bf(b); p[2 * SEQ] = f2bf(c); p[3 * SEQ] = f2bf(d); }
;     else *(u32x2*)(proj + (size_t)m * EIN + n) = pk4(a, b, c, d); }
.LBB0_356:
	s_or_b64 exec, exec, s[16:17]
	v_permlane16_swap_b32_e32 v94, v90
	v_permlane16_swap_b32_e32 v95, v91
	v_permlane16_swap_b32_e32 v96, v92
	v_permlane16_swap_b32_e32 v97, v93
	s_and_saveexec_b64 s[16:17], s[4:5]
	s_cbranch_execz .LBB0_379
	v_cmp_lt_i32_e32 vcc, s69, v152
	s_mov_b64 s[20:21], 0
	s_mov_b64 s[18:19], 0
	s_and_saveexec_b64 s[6:7], vcc
	s_xor_b64 s[6:7], exec, s[6:7]
	v_cmp_ne_u32_e32 vcc, s70, v152
	s_and_b64 s[20:21], vcc, exec
	s_mov_b64 s[18:19], exec
	s_andn2_saveexec_b64 s[22:23], s[6:7]
	v_cmp_eq_u32_e32 vcc, s71, v152
	v_cmp_ne_u32_e64 s[6:7], s71, v152
	s_andn2_b64 s[18:19], s[18:19], exec
	s_and_b64 s[26:27], vcc, exec
	s_andn2_b64 s[20:21], s[20:21], exec
	s_and_b64 s[6:7], s[6:7], exec
	s_or_b64 s[18:19], s[18:19], s[26:27]
	s_or_b64 s[20:21], s[20:21], s[6:7]
	s_or_b64 exec, exec, s[22:23]
	v_or_b32_e32 v98, 64, v153
	s_and_saveexec_b64 s[6:7], s[20:21]
	s_xor_b64 s[6:7], exec, s[6:7]
	s_cbranch_execz .LBB0_363
	v_readlane_b32 s20, v255, 24
	v_readlane_b32 s21, v255, 25
	v_cvt_pk_bf16_f32 v100, v94, v95
	v_cvt_pk_bf16_f32 v101, v96, v97
	v_mov_b64_e32 v[104:105], s[20:21]
	v_mad_i64_i32 v[104:105], s[20:21], v98, s87, v[104:105]
	v_cvt_pk_bf16_f32 v102, v90, v91
	v_cvt_pk_bf16_f32 v103, v92, v93
	v_lshl_add_u64 v[104:105], v[130:131], 1, v[104:105]
	s_andn2_b64 s[18:19], s[18:19], exec
	flat_store_dwordx4 v[104:105], v[100:103]
	v_subrev_u32_e32 v230, 0x998, v130
	v_cmp_gt_u32_e64 s[30:31], 64, v230
	s_and_saveexec_b64 s[36:37], s[30:31]
	v_readlane_b32 s80, v255, 24
	v_readlane_b32 s81, v255, 25
	v_lshrrev_b32_e32 v231, 5, v98
	v_lshlrev_b32_e32 v231, 11, v231
	v_and_b32_e32 v232, 31, v98
	v_lshl_or_b32 v231, v232, 4, v231
	v_lshrrev_b32_e32 v232, 4, v230
	v_lshl_or_b32 v231, v232, 9, v231
	v_and_b32_e32 v232, 15, v230
	v_or_b32_e32 v231, v231, v232
	v_add_u32_e32 v234, 0x9000000, v231
	v_mov_b32_e32 v235, 0
	v_lshl_add_u64 v[236:237], v[234:235], 1, s[80:81]
	flat_store_dwordx4 v[236:237], v[100:103]
	s_or_b64 exec, exec, s[36:37]

; DI bf16_t f2bf(float a) { return (bf16_t)(pk2(a, 0.f) & 0xffffu); }
; DI u32x2 pk4(float a, float b, float c, float d) { u32x2 r; r.x = pk2(a, b); r.y = pk2(c, d); return r; }
; template <class AF, class EF>
; DI void gemm_run(unsigned char* lds, int wv, const AF& af, const bf16_t* __restrict__ Bt, int ldb, int M, int N, int K, const EF& ef, int blk_off) {
;     ...
;         for (int k = 0; k < 4; ++k) {
;           auto r = __builtin_amdgcn_permlane16_swap(__float_as_uint(acc[2 * ip][j][k]), __float_as_uint(acc[2 * ip + 1][j][k]), false, false);
;           lo[k] = __uint_as_float(r[0]); hi[k] = __uint_as_float(r[1]);
;         }
;         int n = n0 + wn * 64 + (2 * ip + (q4 & 1)) * 16 + (q4 >> 1) * 8;
;         int m = m0 + wm * 128 + j * 16 + l15;
;         if (n < N) ef.store8(m, n, lo[0], lo[1], lo[2], lo[3], hi[0], hi[1], hi[2], hi[3]);
;   DI void store(int m, int n, float a, float b, float c, float d) const {
;     int bb = m >> 13, s = m & (SEQ - 1);
;     if (n >= C_VS && n < C_KW) { int e = n - C_VS; bf16_t* p = vsT + ((size_t)(bb * 128 + e)) * SEQ + s; p[0] = f2bf(a); p[SEQ] = f2bf(b); p[2 * SEQ] = f2bf(c); p[3 * SEQ] = f2bf(d); }
;     else if (n >= C_VW && n < C_GATE) { int e = n - C_VW; bf16_t* p = vwT + ((size_t)(bb * 128 + e)) * SEQ + s; p[0] = f2bf(a); p[SEQ] = f2bf(b); p[2 * SEQ] = f2bf(c); p[3 * SEQ] = f2bf(d); }
;     else *(u32x2*)(proj + (size_t)m * EIN + n) = pk4(a, b, c, d); }
.LBB0_379:
	s_or_b64 exec, exec, s[16:17]
	v_permlane16_swap_b32_e32 v86, v82
	v_permlane16_swap_b32_e32 v87, v83
	v_permlane16_swap_b32_e32 v88, v84
	v_permlane16_swap_b32_e32 v89, v85
	s_and_saveexec_b64 s[16:17], s[4:5]
	s_cbranch_execz .LBB0_402
	v_cmp_lt_i32_e32 vcc, s69, v152
	s_mov_b64 s[20:21], 0
	s_mov_b64 s[18:19], 0
	s_and_saveexec_b64 s[6:7], vcc
	s_xor_b64 s[6:7], exec, s[6:7]
	v_cmp_ne_u32_e32 vcc, s70, v152
	s_and_b64 s[20:21], vcc, exec
	s_mov_b64 s[18:19], exec
	s_andn2_saveexec_b64 s[22:23], s[6:7]
	v_cmp_eq_u32_e32 vcc, s71, v152
	v_cmp_ne_u32_e64 s[6:7], s71, v152
	s_andn2_b64 s[18:19], s[18:19], exec
	s_and_b64 s[26:27], vcc, exec
	s_andn2_b64 s[20:21], s[20:21], exec
	s_and_b64 s[6:7], s[6:7], exec
	s_or_b64 s[18:19], s[18:19], s[26:27]
	s_or_b64 s[20:21], s[20:21], s[6:7]
	s_or_b64 exec, exec, s[22:23]
	v_or_b32_e32 v90, 0x50, v153
	s_and_saveexec_b64 s[6:7], s[20:21]
	s_xor_b64 s[6:7], exec, s[6:7]
	s_cbranch_execz .LBB0_386
	v_readlane_b32 s20, v255, 24
	v_readlane_b32 s21, v255, 25
	v_cvt_pk_bf16_f32 v92, v86, v87
	v_cvt_pk_bf16_f32 v93, v88, v89
	v_mov_b64_e32 v[96:97], s[20:21]
	v_mad_i64_i32 v[96:97], s[20:21], v90, s87, v[96:97]
	v_cvt_pk_bf16_f32 v94, v82, v83
	v_cvt_pk_bf16_f32 v95, v84, v85
	v_lshl_add_u64 v[96:97], v[130:131], 1, v[96:97]
	s_andn2_b64 s[18:19], s[18:19], exec
	flat_store_dwordx4 v[96:97], v[92:95]
	v_subrev_u32_e32 v230, 0x998, v130
	v_cmp_gt_u32_e64 s[30:31], 64, v230
	s_and_saveexec_b64 s[36:37], s[30:31]
	v_readlane_b32 s80, v255, 24
	v_readlane_b32 s81, v255, 25
	v_lshrrev_b32_e32 v231, 5, v90
	v_lshlrev_b32_e32 v231, 11, v231
	v_and_b32_e32 v232, 31, v90
	v_lshl_or_b32 v231, v232, 4, v231
	v_lshrrev_b32_e32 v232, 4, v230
	v_lshl_or_b32 v231, v232, 9, v231
	v_and_b32_e32 v232, 15, v230
	v_or_b32_e32 v231, v231, v232
	v_add_u32_e32 v234, 0x9000000, v231
	v_mov_b32_e32 v235, 0
	v_lshl_add_u64 v[236:237], v[234:235], 1, s[80:81]
	flat_store_dwordx4 v[236:237], v[92:95]
	s_or_b64 exec, exec, s[36:37]

; DI bf16_t f2bf(float a) { return (bf16_t)(pk2(a, 0.f) & 0xffffu); }
; DI u32x2 pk4(float a, float b, float c, float d) { u32x2 r; r.x = pk2(a, b); r.y = pk2(c, d); return r; }
; template <class AF, class EF>
; DI void gemm_run(unsigned char* lds, int wv, const AF& af, const bf16_t* __restrict__ Bt, int ldb, int M, int N, int K, const EF& ef, int blk_off) {
;     ...
;         for (int k = 0; k < 4; ++k) {
;           auto r = __builtin_amdgcn_permlane16_swap(__float_as_uint(acc[2 * ip][j][k]), __float_as_uint(acc[2 * ip + 1][j][k]), false, false);
;           lo[k] = __uint_as_float(r[0]); hi[k] = __uint_as_float(r[1]);
;         }
;         int n = n0 + wn * 64 + (2 * ip + (q4 & 1)) * 16 + (q4 >> 1) * 8;
;         int m = m0 + wm * 128 + j * 16 + l15;
;         if (n < N) ef.store8(m, n, lo[0], lo[1], lo[2], lo[3], hi[0], hi[1], hi[2], hi[3]);
;   DI void store(int m, int n, float a, float b, float c, float d) const {
;     int bb = m >> 13, s = m & (SEQ - 1);
;     if (n >= C_VS && n < C_KW) { int e = n - C_VS; bf16_t* p = vsT + ((size_t)(bb * 128 + e)) * SEQ + s; p[0] = f2bf(a); p[SEQ] = f2bf(b); p[2 * SEQ] = f2bf(c); p[3 * SEQ] = f2bf(d); }
;     else if (n >= C_VW && n < C_GATE) { int e = n - C_VW; bf16_t* p = vwT + ((size_t)(bb * 128 + e)) * SEQ + s; p[0] = f2bf(a); p[SEQ] = f2bf(b); p[2 * SEQ] = f2bf(c); p[3 * SEQ] = f2bf(d); }
;     else *(u32x2*)(proj + (size_t)m * EIN + n) = pk4(a, b, c, d); }
.LBB0_402:
	s_or_b64 exec, exec, s[16:17]
	v_permlane16_swap_b32_e32 v78, v74
	v_permlane16_swap_b32_e32 v79, v75
	v_permlane16_swap_b32_e32 v80, v76
	v_permlane16_swap_b32_e32 v81, v77
	s_and_saveexec_b64 s[16:17], s[4:5]
	s_cbranch_execz .LBB0_425
	v_cmp_lt_i32_e32 vcc, s69, v152
	s_mov_b64 s[20:21], 0
	s_mov_b64 s[18:19], 0
	s_and_saveexec_b64 s[6:7], vcc
	s_xor_b64 s[6:7], exec, s[6:7]
	v_cmp_ne_u32_e32 vcc, s70, v152
	s_and_b64 s[20:21], vcc, exec
	s_mov_b64 s[18:19], exec
	s_andn2_saveexec_b64 s[22:23], s[6:7]
	v_cmp_eq_u32_e32 vcc, s71, v152
	v_cmp_ne_u32_e64 s[6:7], s71, v152
	s_andn2_b64 s[18:19], s[18:19], exec
	s_and_b64 s[26:27], vcc, exec
	s_andn2_b64 s[20:21], s[20:21], exec
	s_and_b64 s[6:7], s[6:7], exec
	s_or_b64 s[18:19], s[18:19], s[26:27]
	s_or_b64 s[20:21], s[20:21], s[6:7]
	s_or_b64 exec, exec, s[22:23]
	v_or_b32_e32 v82, 0x60, v153
	s_and_saveexec_b64 s[6:7], s[20:21]
	s_xor_b64 s[6:7], exec, s[6:7]
	s_cbranch_execz .LBB0_409
	v_readlane_b32 s20, v255, 24
	v_readlane_b32 s21, v255, 25
	v_cvt_pk_bf16_f32 v84, v78, v79
	v_cvt_pk_bf16_f32 v85, v80, v81
	v_mov_b64_e32 v[88:89], s[20:21]
	v_mad_i64_i32 v[88:89], s[20:21], v82, s87, v[88:89]
	v_cvt_pk_bf16_f32 v86, v74, v75
	v_cvt_pk_bf16_f32 v87, v76, v77
	v_lshl_add_u64 v[88:89], v[130:131], 1, v[88:89]
	s_andn2_b64 s[18:19], s[18:19], exec
	flat_store_dwordx4 v[88:89], v[84:87]
	v_subrev_u32_e32 v230, 0x998, v130
	v_cmp_gt_u32_e64 s[30:31], 64, v230
	s_and_saveexec_b64 s[36:37], s[30:31]
	v_readlane_b32 s80, v255, 24
	v_readlane_b32 s81, v255, 25
	v_lshrrev_b32_e32 v231, 5, v82
	v_lshlrev_b32_e32 v231, 11, v231
	v_and_b32_e32 v232, 31, v82
	v_lshl_or_b32 v231, v232, 4, v231
	v_lshrrev_b32_e32 v232, 4, v230
	v_lshl_or_b32 v231, v232, 9, v231
	v_and_b32_e32 v232, 15, v230
	v_or_b32_e32 v231, v231, v232
	v_add_u32_e32 v234, 0x9000000, v231
	v_mov_b32_e32 v235, 0
	v_lshl_add_u64 v[236:237], v[234:235], 1, s[80:81]
	flat_store_dwordx4 v[236:237], v[84:87]
	s_or_b64 exec, exec, s[36:37]

; DI bf16_t f2bf(float a) { return (bf16_t)(pk2(a, 0.f) & 0xffffu); }
; DI u32x2 pk4(float a, float b, float c, float d) { u32x2 r; r.x = pk2(a, b); r.y = pk2(c, d); return r; }
; template <class AF, class EF>
; DI void gemm_run(unsigned char* lds, int wv, const AF& af, const bf16_t* __restrict__ Bt, int ldb, int M, int N, int K, const EF& ef, int blk_off) {
;     ...
;         for (int k = 0; k < 4; ++k) {
;           auto r = __builtin_amdgcn_permlane16_swap(__float_as_uint(acc[2 * ip][j][k]), __float_as_uint(acc[2 * ip + 1][j][k]), false, false);
;           lo[k] = __uint_as_float(r[0]); hi[k] = __uint_as_float(r[1]);
;         }
;         int n = n0 + wn * 64 + (2 * ip + (q4 & 1)) * 16 + (q4 >> 1) * 8;
;         int m = m0 + wm * 128 + j * 16 + l15;
;         if (n < N) ef.store8(m, n, lo[0], lo[1], lo[2], lo[3], hi[0], hi[1], hi[2], hi[3]);
;   DI void store(int m, int n, float a, float b, float c, float d) const {
;     int bb = m >> 13, s = m & (SEQ - 1);
;     if (n >= C_VS && n < C_KW) { int e = n - C_VS; bf16_t* p = vsT + ((size_t)(bb * 128 + e)) * SEQ + s; p[0] = f2bf(a); p[SEQ] = f2bf(b); p[2 * SEQ] = f2bf(c); p[3 * SEQ] = f2bf(d); }
;     else if (n >= C_VW && n < C_GATE) { int e = n - C_VW; bf16_t* p = vwT + ((size_t)(bb * 128 + e)) * SEQ + s; p[0] = f2bf(a); p[SEQ] = f2bf(b); p[2 * SEQ] = f2bf(c); p[3 * SEQ] = f2bf(d); }
;     else *(u32x2*)(proj + (size_t)m * EIN + n) = pk4(a, b, c, d); }
.LBB0_425:
	s_or_b64 exec, exec, s[16:17]
	v_permlane16_swap_b32_e32 v70, v66
	v_permlane16_swap_b32_e32 v71, v67
	v_permlane16_swap_b32_e32 v72, v68
	v_permlane16_swap_b32_e32 v73, v69
	s_and_saveexec_b64 s[6:7], s[4:5]
	s_cbranch_execz .LBB0_448
	v_cmp_lt_i32_e32 vcc, s69, v152
	s_mov_b64 s[18:19], 0
	s_mov_b64 s[16:17], 0
	s_and_saveexec_b64 s[4:5], vcc
	s_xor_b64 s[4:5], exec, s[4:5]
	v_cmp_ne_u32_e32 vcc, s70, v152
	s_and_b64 s[18:19], vcc, exec
	s_mov_b64 s[16:17], exec
	s_andn2_saveexec_b64 s[20:21], s[4:5]
	v_cmp_eq_u32_e32 vcc, s71, v152
	v_cmp_ne_u32_e64 s[4:5], s71, v152
	s_andn2_b64 s[16:17], s[16:17], exec
	s_and_b64 s[22:23], vcc, exec
	s_andn2_b64 s[18:19], s[18:19], exec
	s_and_b64 s[4:5], s[4:5], exec
	s_or_b64 s[16:17], s[16:17], s[22:23]
	s_or_b64 s[18:19], s[18:19], s[4:5]
	s_or_b64 exec, exec, s[20:21]
	v_or_b32_e32 v74, 0x70, v153
	s_and_saveexec_b64 s[4:5], s[18:19]
	s_xor_b64 s[4:5], exec, s[4:5]
	s_cbranch_execz .LBB0_432
	v_readlane_b32 s18, v255, 24
	v_readlane_b32 s19, v255, 25
	v_cvt_pk_bf16_f32 v76, v70, v71
	v_cvt_pk_bf16_f32 v77, v72, v73
	v_mov_b64_e32 v[80:81], s[18:19]
	v_mad_i64_i32 v[80:81], s[18:19], v74, s87, v[80:81]
	v_cvt_pk_bf16_f32 v78, v66, v67
	v_cvt_pk_bf16_f32 v79, v68, v69
	v_lshl_add_u64 v[80:81], v[130:131], 1, v[80:81]
	s_andn2_b64 s[16:17], s[16:17], exec
	flat_store_dwordx4 v[80:81], v[76:79]
	v_subrev_u32_e32 v230, 0x998, v130
	v_cmp_gt_u32_e64 s[30:31], 64, v230
	s_and_saveexec_b64 s[36:37], s[30:31]
	v_readlane_b32 s80, v255, 24
	v_readlane_b32 s81, v255, 25
	v_lshrrev_b32_e32 v231, 5, v74
	v_lshlrev_b32_e32 v231, 11, v231
	v_and_b32_e32 v232, 31, v74
	v_lshl_or_b32 v231, v232, 4, v231
	v_lshrrev_b32_e32 v232, 4, v230
	v_lshl_or_b32 v231, v232, 9, v231
	v_and_b32_e32 v232, 15, v230
	v_or_b32_e32 v231, v231, v232
	v_add_u32_e32 v234, 0x9000000, v231
	v_mov_b32_e32 v235, 0
	v_lshl_add_u64 v[236:237], v[234:235], 1, s[80:81]
	flat_store_dwordx4 v[236:237], v[76:79]
	s_or_b64 exec, exec, s[36:37]

; DI bf16_t f2bf(float a) { return (bf16_t)(pk2(a, 0.f) & 0xffffu); }
; DI u32x2 pk4(float a, float b, float c, float d) { u32x2 r; r.x = pk2(a, b); r.y = pk2(c, d); return r; }
; template <class AF, class EF>
; DI void gemm_run(unsigned char* lds, int wv, const AF& af, const bf16_t* __restrict__ Bt, int ldb, int M, int N, int K, const EF& ef, int blk_off) {
;     ...
;         for (int k = 0; k < 4; ++k) {
;           auto r = __builtin_amdgcn_permlane16_swap(__float_as_uint(acc[2 * ip][j][k]), __float_as_uint(acc[2 * ip + 1][j][k]), false, false);
;           lo[k] = __uint_as_float(r[0]); hi[k] = __uint_as_float(r[1]);
;         }
;         int n = n0 + wn * 64 + (2 * ip + (q4 & 1)) * 16 + (q4 >> 1) * 8;
;         int m = m0 + wm * 128 + j * 16 + l15;
;         if (n < N) ef.store8(m, n, lo[0], lo[1], lo[2], lo[3], hi[0], hi[1], hi[2], hi[3]);
;   DI void store(int m, int n, float a, float b, float c, float d) const {
;     int bb = m >> 13, s = m & (SEQ - 1);
;     if (n >= C_VS && n < C_KW) { int e = n - C_VS; bf16_t* p = vsT + ((size_t)(bb * 128 + e)) * SEQ + s; p[0] = f2bf(a); p[SEQ] = f2bf(b); p[2 * SEQ] = f2bf(c); p[3 * SEQ] = f2bf(d); }
;     else if (n >= C_VW && n < C_GATE) { int e = n - C_VW; bf16_t* p = vwT + ((size_t)(bb * 128 + e)) * SEQ + s; p[0] = f2bf(a); p[SEQ] = f2bf(b); p[2 * SEQ] = f2bf(c); p[3 * SEQ] = f2bf(d); }
;     else *(u32x2*)(proj + (size_t)m * EIN + n) = pk4(a, b, c, d); }
.LBB0_455:
	v_readlane_b32 s20, v255, 24
	v_readlane_b32 s21, v255, 25
	v_cvt_pk_bf16_f32 v74, v62, v63
	v_cvt_pk_bf16_f32 v75, v64, v65
	v_mov_b64_e32 v[78:79], s[20:21]
	v_mad_i64_i32 v[78:79], s[20:21], v153, s87, v[78:79]
	v_cvt_pk_bf16_f32 v76, v58, v59
	v_cvt_pk_bf16_f32 v77, v60, v61
	v_lshl_add_u64 v[78:79], v[130:131], 1, v[78:79]
	s_andn2_b64 s[18:19], s[18:19], exec
	flat_store_dwordx4 v[78:79], v[74:77] offset:64
	v_subrev_u32_e32 v230, 0x978, v130
	v_cmp_gt_u32_e64 s[30:31], 64, v230
	s_and_saveexec_b64 s[36:37], s[30:31]
	v_readlane_b32 s80, v255, 24
	v_readlane_b32 s81, v255, 25
	v_lshrrev_b32_e32 v231, 5, v153
	v_lshlrev_b32_e32 v231, 11, v231
	v_and_b32_e32 v232, 31, v153
	v_lshl_or_b32 v231, v232, 4, v231
	v_lshrrev_b32_e32 v232, 4, v230
	v_lshl_or_b32 v231, v232, 9, v231
	v_and_b32_e32 v232, 15, v230
	v_or_b32_e32 v231, v231, v232
	v_add_u32_e32 v234, 0x9000000, v231
	v_mov_b32_e32 v235, 0
	v_lshl_add_u64 v[236:237], v[234:235], 1, s[80:81]
	flat_store_dwordx4 v[236:237], v[74:77]
	s_or_b64 exec, exec, s[36:37]
	s_or_b64 exec, exec, s[6:7]
	s_and_b64 exec, exec, s[18:19]
	s_cbranch_execz .LBB0_471

; DI bf16_t f2bf(float a) { return (bf16_t)(pk2(a, 0.f) & 0xffffu); }
; DI u32x2 pk4(float a, float b, float c, float d) { u32x2 r; r.x = pk2(a, b); r.y = pk2(c, d); return r; }
; template <class AF, class EF>
; DI void gemm_run(unsigned char* lds, int wv, const AF& af, const bf16_t* __restrict__ Bt, int ldb, int M, int N, int K, const EF& ef, int blk_off) {
;     ...
;         for (int k = 0; k < 4; ++k) {
;           auto r = __builtin_amdgcn_permlane16_swap(__float_as_uint(acc[2 * ip][j][k]), __float_as_uint(acc[2 * ip + 1][j][k]), false, false);
;           lo[k] = __uint_as_float(r[0]); hi[k] = __uint_as_float(r[1]);
;         }
;         int n = n0 + wn * 64 + (2 * ip + (q4 & 1)) * 16 + (q4 >> 1) * 8;
;         int m = m0 + wm * 128 + j * 16 + l15;
;         if (n < N) ef.store8(m, n, lo[0], lo[1], lo[2], lo[3], hi[0], hi[1], hi[2], hi[3]);
;   DI void store(int m, int n, float a, float b, float c, float d) const {
;     int bb = m >> 13, s = m & (SEQ - 1);
;     if (n >= C_VS && n < C_KW) { int e = n - C_VS; bf16_t* p = vsT + ((size_t)(bb * 128 + e)) * SEQ + s; p[0] = f2bf(a); p[SEQ] = f2bf(b); p[2 * SEQ] = f2bf(c); p[3 * SEQ] = f2bf(d); }
;     else if (n >= C_VW && n < C_GATE) { int e = n - C_VW; bf16_t* p = vwT + ((size_t)(bb * 128 + e)) * SEQ + s; p[0] = f2bf(a); p[SEQ] = f2bf(b); p[2 * SEQ] = f2bf(c); p[3 * SEQ] = f2bf(d); }
;     else *(u32x2*)(proj + (size_t)m * EIN + n) = pk4(a, b, c, d); }
.LBB0_471:
	s_or_b64 exec, exec, s[16:17]
	v_permlane16_swap_b32_e32 v54, v50
	v_permlane16_swap_b32_e32 v55, v51
	v_permlane16_swap_b32_e32 v56, v52
	v_permlane16_swap_b32_e32 v57, v53
	s_and_saveexec_b64 s[16:17], s[4:5]
	s_cbranch_execz .LBB0_494
	v_cmp_lt_i32_e32 vcc, s69, v152
	s_mov_b64 s[20:21], 0
	s_mov_b64 s[18:19], 0
	s_and_saveexec_b64 s[6:7], vcc
	s_xor_b64 s[6:7], exec, s[6:7]
	v_cmp_ne_u32_e32 vcc, s70, v152
	s_and_b64 s[20:21], vcc, exec
	s_mov_b64 s[18:19], exec
	s_andn2_saveexec_b64 s[22:23], s[6:7]
	v_cmp_eq_u32_e32 vcc, s71, v152
	v_cmp_ne_u32_e64 s[6:7], s71, v152
	s_andn2_b64 s[18:19], s[18:19], exec
	s_and_b64 s[26:27], vcc, exec
	s_andn2_b64 s[20:21], s[20:21], exec
	s_and_b64 s[6:7], s[6:7], exec
	s_or_b64 s[18:19], s[18:19], s[26:27]
	s_or_b64 s[20:21], s[20:21], s[6:7]
	s_or_b64 exec, exec, s[22:23]
	v_or_b32_e32 v58, 16, v153
	s_and_saveexec_b64 s[6:7], s[20:21]
	s_xor_b64 s[6:7], exec, s[6:7]
	s_cbranch_execz .LBB0_478
	v_readlane_b32 s20, v255, 24
	v_readlane_b32 s21, v255, 25
	v_cvt_pk_bf16_f32 v60, v54, v55
	v_cvt_pk_bf16_f32 v61, v56, v57
	v_mov_b64_e32 v[64:65], s[20:21]
	v_mad_i64_i32 v[64:65], s[20:21], v58, s87, v[64:65]
	v_cvt_pk_bf16_f32 v62, v50, v51
	v_cvt_pk_bf16_f32 v63, v52, v53
	v_lshl_add_u64 v[64:65], v[130:131], 1, v[64:65]
	s_andn2_b64 s[18:19], s[18:19], exec
	flat_store_dwordx4 v[64:65], v[60:63] offset:64
	v_subrev_u32_e32 v230, 0x978, v130
	v_cmp_gt_u32_e64 s[30:31], 64, v230
	s_and_saveexec_b64 s[36:37], s[30:31]
	v_readlane_b32 s80, v255, 24
	v_readlane_b32 s81, v255, 25
	v_lshrrev_b32_e32 v231, 5, v58
	v_lshlrev_b32_e32 v231, 11, v231
	v_and_b32_e32 v232, 31, v58
	v_lshl_or_b32 v231, v232, 4, v231
	v_lshrrev_b32_e32 v232, 4, v230
	v_lshl_or_b32 v231, v232, 9, v231
	v_and_b32_e32 v232, 15, v230
	v_or_b32_e32 v231, v231, v232
	v_add_u32_e32 v234, 0x9000000, v231
	v_mov_b32_e32 v235, 0
	v_lshl_add_u64 v[236:237], v[234:235], 1, s[80:81]
	flat_store_dwordx4 v[236:237], v[60:63]
	s_or_b64 exec, exec, s[36:37]

; DI bf16_t f2bf(float a) { return (bf16_t)(pk2(a, 0.f) & 0xffffu); }
; DI u32x2 pk4(float a, float b, float c, float d) { u32x2 r; r.x = pk2(a, b); r.y = pk2(c, d); return r; }
; template <class AF, class EF>
; DI void gemm_run(unsigned char* lds, int wv, const AF& af, const bf16_t* __restrict__ Bt, int ldb, int M, int N, int K, const EF& ef, int blk_off) {
;     ...
;         for (int k = 0; k < 4; ++k) {
;           auto r = __builtin_amdgcn_permlane16_swap(__float_as_uint(acc[2 * ip][j][k]), __float_as_uint(acc[2 * ip + 1][j][k]), false, false);
;           lo[k] = __uint_as_float(r[0]); hi[k] = __uint_as_float(r[1]);
;         }
;         int n = n0 + wn * 64 + (2 * ip + (q4 & 1)) * 16 + (q4 >> 1) * 8;
;         int m = m0 + wm * 128 + j * 16 + l15;
;         if (n < N) ef.store8(m, n, lo[0], lo[1], lo[2], lo[3], hi[0], hi[1], hi[2], hi[3]);
;   DI void store(int m, int n, float a, float b, float c, float d) const {
;     int bb = m >> 13, s = m & (SEQ - 1);
;     if (n >= C_VS && n < C_KW) { int e = n - C_VS; bf16_t* p = vsT + ((size_t)(bb * 128 + e)) * SEQ + s; p[0] = f2bf(a); p[SEQ] = f2bf(b); p[2 * SEQ] = f2bf(c); p[3 * SEQ] = f2bf(d); }
;     else if (n >= C_VW && n < C_GATE) { int e = n - C_VW; bf16_t* p = vwT + ((size_t)(bb * 128 + e)) * SEQ + s; p[0] = f2bf(a); p[SEQ] = f2bf(b); p[2 * SEQ] = f2bf(c); p[3 * SEQ] = f2bf(d); }
;     else *(u32x2*)(proj + (size_t)m * EIN + n) = pk4(a, b, c, d); }
.LBB0_494:
	s_or_b64 exec, exec, s[16:17]
	v_permlane16_swap_b32_e32 v46, v42
	v_permlane16_swap_b32_e32 v47, v43
	v_permlane16_swap_b32_e32 v48, v44
	v_permlane16_swap_b32_e32 v49, v45
	s_and_saveexec_b64 s[16:17], s[4:5]
	s_cbranch_execz .LBB0_517
	v_cmp_lt_i32_e32 vcc, s69, v152
	s_mov_b64 s[20:21], 0
	s_mov_b64 s[18:19], 0
	s_and_saveexec_b64 s[6:7], vcc
	s_xor_b64 s[6:7], exec, s[6:7]
	v_cmp_ne_u32_e32 vcc, s70, v152
	s_and_b64 s[20:21], vcc, exec
	s_mov_b64 s[18:19], exec
	s_andn2_saveexec_b64 s[22:23], s[6:7]
	v_cmp_eq_u32_e32 vcc, s71, v152
	v_cmp_ne_u32_e64 s[6:7], s71, v152
	s_andn2_b64 s[18:19], s[18:19], exec
	s_and_b64 s[26:27], vcc, exec
	s_andn2_b64 s[20:21], s[20:21], exec
	s_and_b64 s[6:7], s[6:7], exec
	s_or_b64 s[18:19], s[18:19], s[26:27]
	s_or_b64 s[20:21], s[20:21], s[6:7]
	s_or_b64 exec, exec, s[22:23]
	v_or_b32_e32 v50, 32, v153
	s_and_saveexec_b64 s[6:7], s[20:21]
	s_xor_b64 s[6:7], exec, s[6:7]
	s_cbranch_execz .LBB0_501
	v_readlane_b32 s20, v255, 24
	v_readlane_b32 s21, v255, 25
	v_cvt_pk_bf16_f32 v52, v46, v47
	v_cvt_pk_bf16_f32 v53, v48, v49
	v_mov_b64_e32 v[56:57], s[20:21]
	v_mad_i64_i32 v[56:57], s[20:21], v50, s87, v[56:57]
	v_cvt_pk_bf16_f32 v54, v42, v43
	v_cvt_pk_bf16_f32 v55, v44, v45
	v_lshl_add_u64 v[56:57], v[130:131], 1, v[56:57]
	s_andn2_b64 s[18:19], s[18:19], exec
	flat_store_dwordx4 v[56:57], v[52:55] offset:64
	v_subrev_u32_e32 v230, 0x978, v130
	v_cmp_gt_u32_e64 s[30:31], 64, v230
	s_and_saveexec_b64 s[36:37], s[30:31]
	v_readlane_b32 s80, v255, 24
	v_readlane_b32 s81, v255, 25
	v_lshrrev_b32_e32 v231, 5, v50
	v_lshlrev_b32_e32 v231, 11, v231
	v_and_b32_e32 v232, 31, v50
	v_lshl_or_b32 v231, v232, 4, v231
	v_lshrrev_b32_e32 v232, 4, v230
	v_lshl_or_b32 v231, v232, 9, v231
	v_and_b32_e32 v232, 15, v230
	v_or_b32_e32 v231, v231, v232
	v_add_u32_e32 v234, 0x9000000, v231
	v_mov_b32_e32 v235, 0
	v_lshl_add_u64 v[236:237], v[234:235], 1, s[80:81]
	flat_store_dwordx4 v[236:237], v[52:55]
	s_or_b64 exec, exec, s[36:37]

; DI bf16_t f2bf(float a) { return (bf16_t)(pk2(a, 0.f) & 0xffffu); }
; DI u32x2 pk4(float a, float b, float c, float d) { u32x2 r; r.x = pk2(a, b); r.y = pk2(c, d); return r; }
; template <class AF, class EF>
; DI void gemm_run(unsigned char* lds, int wv, const AF& af, const bf16_t* __restrict__ Bt, int ldb, int M, int N, int K, const EF& ef, int blk_off) {
;     ...
;         for (int k = 0; k < 4; ++k) {
;           auto r = __builtin_amdgcn_permlane16_swap(__float_as_uint(acc[2 * ip][j][k]), __float_as_uint(acc[2 * ip + 1][j][k]), false, false);
;           lo[k] = __uint_as_float(r[0]); hi[k] = __uint_as_float(r[1]);
;         }
;         int n = n0 + wn * 64 + (2 * ip + (q4 & 1)) * 16 + (q4 >> 1) * 8;
;         int m = m0 + wm * 128 + j * 16 + l15;
;         if (n < N) ef.store8(m, n, lo[0], lo[1], lo[2], lo[3], hi[0], hi[1], hi[2], hi[3]);
;   DI void store(int m, int n, float a, float b, float c, float d) const {
;     int bb = m >> 13, s = m & (SEQ - 1);
;     if (n >= C_VS && n < C_KW) { int e = n - C_VS; bf16_t* p = vsT + ((size_t)(bb * 128 + e)) * SEQ + s; p[0] = f2bf(a); p[SEQ] = f2bf(b); p[2 * SEQ] = f2bf(c); p[3 * SEQ] = f2bf(d); }
;     else if (n >= C_VW && n < C_GATE) { int e = n - C_VW; bf16_t* p = vwT + ((size_t)(bb * 128 + e)) * SEQ + s; p[0] = f2bf(a); p[SEQ] = f2bf(b); p[2 * SEQ] = f2bf(c); p[3 * SEQ] = f2bf(d); }
;     else *(u32x2*)(proj + (size_t)m * EIN + n) = pk4(a, b, c, d); }
.LBB0_517:
	s_or_b64 exec, exec, s[16:17]
	v_permlane16_swap_b32_e32 v38, v34
	v_permlane16_swap_b32_e32 v39, v35
	v_permlane16_swap_b32_e32 v40, v36
	v_permlane16_swap_b32_e32 v41, v37
	s_and_saveexec_b64 s[16:17], s[4:5]
	s_cbranch_execz .LBB0_540
	v_cmp_lt_i32_e32 vcc, s69, v152
	s_mov_b64 s[20:21], 0
	s_mov_b64 s[18:19], 0
	s_and_saveexec_b64 s[6:7], vcc
	s_xor_b64 s[6:7], exec, s[6:7]
	v_cmp_ne_u32_e32 vcc, s70, v152
	s_and_b64 s[20:21], vcc, exec
	s_mov_b64 s[18:19], exec
	s_andn2_saveexec_b64 s[22:23], s[6:7]
	v_cmp_eq_u32_e32 vcc, s71, v152
	v_cmp_ne_u32_e64 s[6:7], s71, v152
	s_andn2_b64 s[18:19], s[18:19], exec
	s_and_b64 s[26:27], vcc, exec
	s_andn2_b64 s[20:21], s[20:21], exec
	s_and_b64 s[6:7], s[6:7], exec
	s_or_b64 s[18:19], s[18:19], s[26:27]
	s_or_b64 s[20:21], s[20:21], s[6:7]
	s_or_b64 exec, exec, s[22:23]
	v_or_b32_e32 v42, 48, v153
	s_and_saveexec_b64 s[6:7], s[20:21]
	s_xor_b64 s[6:7], exec, s[6:7]
	s_cbranch_execz .LBB0_524
	v_readlane_b32 s20, v255, 24
	v_readlane_b32 s21, v255, 25
	v_cvt_pk_bf16_f32 v44, v38, v39
	v_cvt_pk_bf16_f32 v45, v40, v41
	v_mov_b64_e32 v[48:49], s[20:21]
	v_mad_i64_i32 v[48:49], s[20:21], v42, s87, v[48:49]
	v_cvt_pk_bf16_f32 v46, v34, v35
	v_cvt_pk_bf16_f32 v47, v36, v37
	v_lshl_add_u64 v[48:49], v[130:131], 1, v[48:49]
	s_andn2_b64 s[18:19], s[18:19], exec
	flat_store_dwordx4 v[48:49], v[44:47] offset:64
	v_subrev_u32_e32 v230, 0x978, v130
	v_cmp_gt_u32_e64 s[30:31], 64, v230
	s_and_saveexec_b64 s[36:37], s[30:31]
	v_readlane_b32 s80, v255, 24
	v_readlane_b32 s81, v255, 25
	v_lshrrev_b32_e32 v231, 5, v42
	v_lshlrev_b32_e32 v231, 11, v231
	v_and_b32_e32 v232, 31, v42
	v_lshl_or_b32 v231, v232, 4, v231
	v_lshrrev_b32_e32 v232, 4, v230
	v_lshl_or_b32 v231, v232, 9, v231
	v_and_b32_e32 v232, 15, v230
	v_or_b32_e32 v231, v231, v232
	v_add_u32_e32 v234, 0x9000000, v231
	v_mov_b32_e32 v235, 0
	v_lshl_add_u64 v[236:237], v[234:235], 1, s[80:81]
	flat_store_dwordx4 v[236:237], v[44:47]
	s_or_b64 exec, exec, s[36:37]

; DI bf16_t f2bf(float a) { return (bf16_t)(pk2(a, 0.f) & 0xffffu); }
; DI u32x2 pk4(float a, float b, float c, float d) { u32x2 r; r.x = pk2(a, b); r.y = pk2(c, d); return r; }
; template <class AF, class EF>
; DI void gemm_run(unsigned char* lds, int wv, const AF& af, const bf16_t* __restrict__ Bt, int ldb, int M, int N, int K, const EF& ef, int blk_off) {
;     ...
;         for (int k = 0; k < 4; ++k) {
;           auto r = __builtin_amdgcn_permlane16_swap(__float_as_uint(acc[2 * ip][j][k]), __float_as_uint(acc[2 * ip + 1][j][k]), false, false);
;           lo[k] = __uint_as_float(r[0]); hi[k] = __uint_as_float(r[1]);
;         }
;         int n = n0 + wn * 64 + (2 * ip + (q4 & 1)) * 16 + (q4 >> 1) * 8;
;         int m = m0 + wm * 128 + j * 16 + l15;
;         if (n < N) ef.store8(m, n, lo[0], lo[1], lo[2], lo[3], hi[0], hi[1], hi[2], hi[3]);
;   DI void store(int m, int n, float a, float b, float c, float d) const {
;     int bb = m >> 13, s = m & (SEQ - 1);
;     if (n >= C_VS && n < C_KW) { int e = n - C_VS; bf16_t* p = vsT + ((size_t)(bb * 128 + e)) * SEQ + s; p[0] = f2bf(a); p[SEQ] = f2bf(b); p[2 * SEQ] = f2bf(c); p[3 * SEQ] = f2bf(d); }
;     else if (n >= C_VW && n < C_GATE) { int e = n - C_VW; bf16_t* p = vwT + ((size_t)(bb * 128 + e)) * SEQ + s; p[0] = f2bf(a); p[SEQ] = f2bf(b); p[2 * SEQ] = f2bf(c); p[3 * SEQ] = f2bf(d); }
;     else *(u32x2*)(proj + (size_t)m * EIN + n) = pk4(a, b, c, d); }
.LBB0_540:
	s_or_b64 exec, exec, s[16:17]
	v_permlane16_swap_b32_e32 v30, v26
	v_permlane16_swap_b32_e32 v31, v27
	v_permlane16_swap_b32_e32 v32, v28
	v_permlane16_swap_b32_e32 v33, v29
	s_and_saveexec_b64 s[16:17], s[4:5]
	s_cbranch_execz .LBB0_563
	v_cmp_lt_i32_e32 vcc, s69, v152
	s_mov_b64 s[20:21], 0
	s_mov_b64 s[18:19], 0
	s_and_saveexec_b64 s[6:7], vcc
	s_xor_b64 s[6:7], exec, s[6:7]
	v_cmp_ne_u32_e32 vcc, s70, v152
	s_and_b64 s[20:21], vcc, exec
	s_mov_b64 s[18:19], exec
	s_andn2_saveexec_b64 s[22:23], s[6:7]
	v_cmp_eq_u32_e32 vcc, s71, v152
	v_cmp_ne_u32_e64 s[6:7], s71, v152
	s_andn2_b64 s[18:19], s[18:19], exec
	s_and_b64 s[26:27], vcc, exec
	s_andn2_b64 s[20:21], s[20:21], exec
	s_and_b64 s[6:7], s[6:7], exec
	s_or_b64 s[18:19], s[18:19], s[26:27]
	s_or_b64 s[20:21], s[20:21], s[6:7]
	s_or_b64 exec, exec, s[22:23]
	v_or_b32_e32 v34, 64, v153
	s_and_saveexec_b64 s[6:7], s[20:21]
	s_xor_b64 s[6:7], exec, s[6:7]
	s_cbranch_execz .LBB0_547
	v_readlane_b32 s20, v255, 24
	v_readlane_b32 s21, v255, 25
	v_cvt_pk_bf16_f32 v36, v30, v31
	v_cvt_pk_bf16_f32 v37, v32, v33
	v_mov_b64_e32 v[40:41], s[20:21]
	v_mad_i64_i32 v[40:41], s[20:21], v34, s87, v[40:41]
	v_cvt_pk_bf16_f32 v38, v26, v27
	v_cvt_pk_bf16_f32 v39, v28, v29
	v_lshl_add_u64 v[40:41], v[130:131], 1, v[40:41]
	s_andn2_b64 s[18:19], s[18:19], exec
	flat_store_dwordx4 v[40:41], v[36:39] offset:64
	v_subrev_u32_e32 v230, 0x978, v130
	v_cmp_gt_u32_e64 s[30:31], 64, v230
	s_and_saveexec_b64 s[36:37], s[30:31]
	v_readlane_b32 s80, v255, 24
	v_readlane_b32 s81, v255, 25
	v_lshrrev_b32_e32 v231, 5, v34
	v_lshlrev_b32_e32 v231, 11, v231
	v_and_b32_e32 v232, 31, v34
	v_lshl_or_b32 v231, v232, 4, v231
	v_lshrrev_b32_e32 v232, 4, v230
	v_lshl_or_b32 v231, v232, 9, v231
	v_and_b32_e32 v232, 15, v230
	v_or_b32_e32 v231, v231, v232
	v_add_u32_e32 v234, 0x9000000, v231
	v_mov_b32_e32 v235, 0
	v_lshl_add_u64 v[236:237], v[234:235], 1, s[80:81]
	flat_store_dwordx4 v[236:237], v[36:39]
	s_or_b64 exec, exec, s[36:37]

; DI bf16_t f2bf(float a) { return (bf16_t)(pk2(a, 0.f) & 0xffffu); }
; DI u32x2 pk4(float a, float b, float c, float d) { u32x2 r; r.x = pk2(a, b); r.y = pk2(c, d); return r; }
; template <class AF, class EF>
; DI void gemm_run(unsigned char* lds, int wv, const AF& af, const bf16_t* __restrict__ Bt, int ldb, int M, int N, int K, const EF& ef, int blk_off) {
;     ...
;         for (int k = 0; k < 4; ++k) {
;           auto r = __builtin_amdgcn_permlane16_swap(__float_as_uint(acc[2 * ip][j][k]), __float_as_uint(acc[2 * ip + 1][j][k]), false, false);
;           lo[k] = __uint_as_float(r[0]); hi[k] = __uint_as_float(r[1]);
;         }
;         int n = n0 + wn * 64 + (2 * ip + (q4 & 1)) * 16 + (q4 >> 1) * 8;
;         int m = m0 + wm * 128 + j * 16 + l15;
;         if (n < N) ef.store8(m, n, lo[0], lo[1], lo[2], lo[3], hi[0], hi[1], hi[2], hi[3]);
;   DI void store(int m, int n, float a, float b, float c, float d) const {
;     int bb = m >> 13, s = m & (SEQ - 1);
;     if (n >= C_VS && n < C_KW) { int e = n - C_VS; bf16_t* p = vsT + ((size_t)(bb * 128 + e)) * SEQ + s; p[0] = f2bf(a); p[SEQ] = f2bf(b); p[2 * SEQ] = f2bf(c); p[3 * SEQ] = f2bf(d); }
;     else if (n >= C_VW && n < C_GATE) { int e = n - C_VW; bf16_t* p = vwT + ((size_t)(bb * 128 + e)) * SEQ + s; p[0] = f2bf(a); p[SEQ] = f2bf(b); p[2 * SEQ] = f2bf(c); p[3 * SEQ] = f2bf(d); }
;     else *(u32x2*)(proj + (size_t)m * EIN + n) = pk4(a, b, c, d); }
.LBB0_563:
	s_or_b64 exec, exec, s[16:17]
	v_permlane16_swap_b32_e32 v22, v18
	v_permlane16_swap_b32_e32 v23, v19
	v_permlane16_swap_b32_e32 v24, v20
	v_permlane16_swap_b32_e32 v25, v21
	s_and_saveexec_b64 s[16:17], s[4:5]
	s_cbranch_execz .LBB0_586
	v_cmp_lt_i32_e32 vcc, s69, v152
	s_mov_b64 s[20:21], 0
	s_mov_b64 s[18:19], 0
	s_and_saveexec_b64 s[6:7], vcc
	s_xor_b64 s[6:7], exec, s[6:7]
	v_cmp_ne_u32_e32 vcc, s70, v152
	s_and_b64 s[20:21], vcc, exec
	s_mov_b64 s[18:19], exec
	s_andn2_saveexec_b64 s[22:23], s[6:7]
	v_cmp_eq_u32_e32 vcc, s71, v152
	v_cmp_ne_u32_e64 s[6:7], s71, v152
	s_andn2_b64 s[18:19], s[18:19], exec
	s_and_b64 s[26:27], vcc, exec
	s_andn2_b64 s[20:21], s[20:21], exec
	s_and_b64 s[6:7], s[6:7], exec
	s_or_b64 s[18:19], s[18:19], s[26:27]
	s_or_b64 s[20:21], s[20:21], s[6:7]
	s_or_b64 exec, exec, s[22:23]
	v_or_b32_e32 v26, 0x50, v153
	s_and_saveexec_b64 s[6:7], s[20:21]
	s_xor_b64 s[6:7], exec, s[6:7]
	s_cbranch_execz .LBB0_570
	v_readlane_b32 s20, v255, 24
	v_readlane_b32 s21, v255, 25
	v_cvt_pk_bf16_f32 v28, v22, v23
	v_cvt_pk_bf16_f32 v29, v24, v25
	v_mov_b64_e32 v[32:33], s[20:21]
	v_mad_i64_i32 v[32:33], s[20:21], v26, s87, v[32:33]
	v_cvt_pk_bf16_f32 v30, v18, v19
	v_cvt_pk_bf16_f32 v31, v20, v21
	v_lshl_add_u64 v[32:33], v[130:131], 1, v[32:33]
	s_andn2_b64 s[18:19], s[18:19], exec
	flat_store_dwordx4 v[32:33], v[28:31] offset:64
	v_subrev_u32_e32 v230, 0x978, v130
	v_cmp_gt_u32_e64 s[30:31], 64, v230
	s_and_saveexec_b64 s[36:37], s[30:31]
	v_readlane_b32 s80, v255, 24
	v_readlane_b32 s81, v255, 25
	v_lshrrev_b32_e32 v231, 5, v26
	v_lshlrev_b32_e32 v231, 11, v231
	v_and_b32_e32 v232, 31, v26
	v_lshl_or_b32 v231, v232, 4, v231
	v_lshrrev_b32_e32 v232, 4, v230
	v_lshl_or_b32 v231, v232, 9, v231
	v_and_b32_e32 v232, 15, v230
	v_or_b32_e32 v231, v231, v232
	v_add_u32_e32 v234, 0x9000000, v231
	v_mov_b32_e32 v235, 0
	v_lshl_add_u64 v[236:237], v[234:235], 1, s[80:81]
	flat_store_dwordx4 v[236:237], v[28:31]
	s_or_b64 exec, exec, s[36:37]

; DI bf16_t f2bf(float a) { return (bf16_t)(pk2(a, 0.f) & 0xffffu); }
; DI u32x2 pk4(float a, float b, float c, float d) { u32x2 r; r.x = pk2(a, b); r.y = pk2(c, d); return r; }
; template <class AF, class EF>
; DI void gemm_run(unsigned char* lds, int wv, const AF& af, const bf16_t* __restrict__ Bt, int ldb, int M, int N, int K, const EF& ef, int blk_off) {
;     ...
;         for (int k = 0; k < 4; ++k) {
;           auto r = __builtin_amdgcn_permlane16_swap(__float_as_uint(acc[2 * ip][j][k]), __float_as_uint(acc[2 * ip + 1][j][k]), false, false);
;           lo[k] = __uint_as_float(r[0]); hi[k] = __uint_as_float(r[1]);
;         }
;         int n = n0 + wn * 64 + (2 * ip + (q4 & 1)) * 16 + (q4 >> 1) * 8;
;         int m = m0 + wm * 128 + j * 16 + l15;
;         if (n < N) ef.store8(m, n, lo[0], lo[1], lo[2], lo[3], hi[0], hi[1], hi[2], hi[3]);
;   DI void store(int m, int n, float a, float b, float c, float d) const {
;     int bb = m >> 13, s = m & (SEQ - 1);
;     if (n >= C_VS && n < C_KW) { int e = n - C_VS; bf16_t* p = vsT + ((size_t)(bb * 128 + e)) * SEQ + s; p[0] = f2bf(a); p[SEQ] = f2bf(b); p[2 * SEQ] = f2bf(c); p[3 * SEQ] = f2bf(d); }
;     else if (n >= C_VW && n < C_GATE) { int e = n - C_VW; bf16_t* p = vwT + ((size_t)(bb * 128 + e)) * SEQ + s; p[0] = f2bf(a); p[SEQ] = f2bf(b); p[2 * SEQ] = f2bf(c); p[3 * SEQ] = f2bf(d); }
;     else *(u32x2*)(proj + (size_t)m * EIN + n) = pk4(a, b, c, d); }
.LBB0_586:
	s_or_b64 exec, exec, s[16:17]
	v_permlane16_swap_b32_e32 v14, v10
	v_permlane16_swap_b32_e32 v15, v11
	v_permlane16_swap_b32_e32 v16, v12
	v_permlane16_swap_b32_e32 v17, v13
	s_and_saveexec_b64 s[16:17], s[4:5]
	s_cbranch_execz .LBB0_609
	v_cmp_lt_i32_e32 vcc, s69, v152
	s_mov_b64 s[20:21], 0
	s_mov_b64 s[18:19], 0
	s_and_saveexec_b64 s[6:7], vcc
	s_xor_b64 s[6:7], exec, s[6:7]
	v_cmp_ne_u32_e32 vcc, s70, v152
	s_and_b64 s[20:21], vcc, exec
	s_mov_b64 s[18:19], exec
	s_andn2_saveexec_b64 s[22:23], s[6:7]
	v_cmp_eq_u32_e32 vcc, s71, v152
	v_cmp_ne_u32_e64 s[6:7], s71, v152
	s_andn2_b64 s[18:19], s[18:19], exec
	s_and_b64 s[26:27], vcc, exec
	s_andn2_b64 s[20:21], s[20:21], exec
	s_and_b64 s[6:7], s[6:7], exec
	s_or_b64 s[18:19], s[18:19], s[26:27]
	s_or_b64 s[20:21], s[20:21], s[6:7]
	s_or_b64 exec, exec, s[22:23]
	v_or_b32_e32 v18, 0x60, v153
	s_and_saveexec_b64 s[6:7], s[20:21]
	s_xor_b64 s[6:7], exec, s[6:7]
	s_cbranch_execz .LBB0_593
	v_readlane_b32 s20, v255, 24
	v_readlane_b32 s21, v255, 25
	v_cvt_pk_bf16_f32 v20, v14, v15
	v_cvt_pk_bf16_f32 v21, v16, v17
	v_mov_b64_e32 v[24:25], s[20:21]
	v_mad_i64_i32 v[24:25], s[20:21], v18, s87, v[24:25]
	v_cvt_pk_bf16_f32 v22, v10, v11
	v_cvt_pk_bf16_f32 v23, v12, v13
	v_lshl_add_u64 v[24:25], v[130:131], 1, v[24:25]
	s_andn2_b64 s[18:19], s[18:19], exec
	flat_store_dwordx4 v[24:25], v[20:23] offset:64
	v_subrev_u32_e32 v230, 0x978, v130
	v_cmp_gt_u32_e64 s[30:31], 64, v230
	s_and_saveexec_b64 s[36:37], s[30:31]
	v_readlane_b32 s80, v255, 24
	v_readlane_b32 s81, v255, 25
	v_lshrrev_b32_e32 v231, 5, v18
	v_lshlrev_b32_e32 v231, 11, v231
	v_and_b32_e32 v232, 31, v18
	v_lshl_or_b32 v231, v232, 4, v231
	v_lshrrev_b32_e32 v232, 4, v230
	v_lshl_or_b32 v231, v232, 9, v231
	v_and_b32_e32 v232, 15, v230
	v_or_b32_e32 v231, v231, v232
	v_add_u32_e32 v234, 0x9000000, v231
	v_mov_b32_e32 v235, 0
	v_lshl_add_u64 v[236:237], v[234:235], 1, s[80:81]
	flat_store_dwordx4 v[236:237], v[20:23]
	s_or_b64 exec, exec, s[36:37]

; DI bf16_t f2bf(float a) { return (bf16_t)(pk2(a, 0.f) & 0xffffu); }
; DI u32x2 pk4(float a, float b, float c, float d) { u32x2 r; r.x = pk2(a, b); r.y = pk2(c, d); return r; }
; template <class AF, class EF>
; DI void gemm_run(unsigned char* lds, int wv, const AF& af, const bf16_t* __restrict__ Bt, int ldb, int M, int N, int K, const EF& ef, int blk_off) {
;     ...
;         for (int k = 0; k < 4; ++k) {
;           auto r = __builtin_amdgcn_permlane16_swap(__float_as_uint(acc[2 * ip][j][k]), __float_as_uint(acc[2 * ip + 1][j][k]), false, false);
;           lo[k] = __uint_as_float(r[0]); hi[k] = __uint_as_float(r[1]);
;         }
;         int n = n0 + wn * 64 + (2 * ip + (q4 & 1)) * 16 + (q4 >> 1) * 8;
;         int m = m0 + wm * 128 + j * 16 + l15;
;         if (n < N) ef.store8(m, n, lo[0], lo[1], lo[2], lo[3], hi[0], hi[1], hi[2], hi[3]);
;   DI void store(int m, int n, float a, float b, float c, float d) const {
;     int bb = m >> 13, s = m & (SEQ - 1);
;     if (n >= C_VS && n < C_KW) { int e = n - C_VS; bf16_t* p = vsT + ((size_t)(bb * 128 + e)) * SEQ + s; p[0] = f2bf(a); p[SEQ] = f2bf(b); p[2 * SEQ] = f2bf(c); p[3 * SEQ] = f2bf(d); }
;     else if (n >= C_VW && n < C_GATE) { int e = n - C_VW; bf16_t* p = vwT + ((size_t)(bb * 128 + e)) * SEQ + s; p[0] = f2bf(a); p[SEQ] = f2bf(b); p[2 * SEQ] = f2bf(c); p[3 * SEQ] = f2bf(d); }
;     else *(u32x2*)(proj + (size_t)m * EIN + n) = pk4(a, b, c, d); }
.LBB0_609:
	s_or_b64 exec, exec, s[16:17]
	v_permlane16_swap_b32_e32 v2, v6
	v_permlane16_swap_b32_e32 v3, v7
	v_permlane16_swap_b32_e32 v4, v8
	v_permlane16_swap_b32_e32 v5, v9
	s_and_saveexec_b64 s[6:7], s[4:5]
	s_cbranch_execz .LBB0_259
	v_cmp_lt_i32_e32 vcc, s69, v152
	s_mov_b64 s[18:19], 0
	s_mov_b64 s[16:17], 0
	s_and_saveexec_b64 s[4:5], vcc
	s_xor_b64 s[4:5], exec, s[4:5]
	v_cmp_ne_u32_e32 vcc, s70, v152
	s_and_b64 s[18:19], vcc, exec
	s_mov_b64 s[16:17], exec
	s_or_saveexec_b64 s[20:21], s[4:5]
	v_cmp_ne_u32_e32 vcc, s71, v152
	s_xor_b64 exec, exec, s[20:21]
	v_cmp_eq_u32_e64 s[4:5], s71, v152
	s_andn2_b64 s[16:17], s[16:17], exec
	s_and_b64 s[4:5], s[4:5], exec
	s_or_b64 s[16:17], s[16:17], s[4:5]
	s_andn2_b64 s[4:5], s[18:19], exec
	s_and_b64 s[18:19], vcc, exec
	s_or_b64 s[18:19], s[4:5], s[18:19]
	s_or_b64 exec, exec, s[20:21]
	v_or_b32_e32 v10, 0x70, v153
	s_and_saveexec_b64 s[4:5], s[18:19]
	s_xor_b64 s[4:5], exec, s[4:5]
	s_cbranch_execz .LBB0_616
	v_readlane_b32 s18, v255, 24
	v_readlane_b32 s19, v255, 25
	v_cvt_pk_bf16_f32 v12, v2, v3
	v_cvt_pk_bf16_f32 v13, v4, v5
	v_mov_b64_e32 v[16:17], s[18:19]
	v_mad_i64_i32 v[16:17], s[18:19], v10, s87, v[16:17]
	v_cvt_pk_bf16_f32 v14, v6, v7
	v_cvt_pk_bf16_f32 v15, v8, v9
	v_lshl_add_u64 v[16:17], v[130:131], 1, v[16:17]
	s_andn2_b64 s[16:17], s[16:17], exec
	flat_store_dwordx4 v[16:17], v[12:15] offset:64
	v_subrev_u32_e32 v230, 0x978, v130
	v_cmp_gt_u32_e64 s[30:31], 64, v230
	s_and_saveexec_b64 s[36:37], s[30:31]
	v_readlane_b32 s80, v255, 24
	v_readlane_b32 s81, v255, 25
	v_lshrrev_b32_e32 v231, 5, v10
	v_lshlrev_b32_e32 v231, 11, v231
	v_and_b32_e32 v232, 31, v10
	v_lshl_or_b32 v231, v232, 4, v231
	v_lshrrev_b32_e32 v232, 4, v230
	v_lshl_or_b32 v231, v232, 9, v231
	v_and_b32_e32 v232, 15, v230
	v_or_b32_e32 v231, v231, v232
	v_add_u32_e32 v234, 0x9000000, v231
	v_mov_b32_e32 v235, 0
	v_lshl_add_u64 v[236:237], v[234:235], 1, s[80:81]
	flat_store_dwordx4 v[236:237], v[12:15]
	s_or_b64 exec, exec, s[36:37]

; template <class T> DI T* opqp(T* p) { unsigned long long v = (unsigned long long)p; asm volatile("" : "+s"(v)); return (T*)v; }
; #define P kparams()
; __global__ void __launch_bounds__(NTHREADS) mega(Params P0) {
;     ...
; #pragma unroll 1
;   for (int l = 0; l < 4; ++l) {
;     const int i2 = l >> 1;
;     unsigned char* ws = opqp(P->ws);
;     bf16_t* hb = (bf16_t*)(ws + OFF_HB);
;     bf16_t* ao = (bf16_t*)(ws + OFF_AO);
;     unsigned char* U = ws + OFF_U;
;     unsigned char* WT = ws + OFF_WT;
;     const float* ada = (const float*)(ws + OFF_MISC + MS_ADA);
;     const float* adal = ada + (size_t)l * 4 * 6144;
;     const float* xin = (l == 0) ? P->in[0] : P->out;
;     if ((l & 1) == 0) {
;       bf16_t* proj = (bf16_t*)(U + U_PROJ);
.Ltramp109:
	s_branch .LBB0_109

; #define MFMA32(a, b, c) __builtin_amdgcn_mfma_f32_32x32x16_bf16((a), (b), (c), 0, 0, 0)
; DI float bf2f(bf16_t v) { return __uint_as_float(((unsigned)v) << 16); }
; DI unsigned fkey(float f) { unsigned u = __float_as_uint(f); return (u & 0x80000000u) ? ~u : (u | 0x80000000u); }
; DI void dsa_index_phase(unsigned char* lds, KParamPtr P, int wv) {
;     ...
;   for (int item = blockIdx.x; item < 8192; item += gridDim.x) {
;     const int b = (item & 7) >> 1, t0 = (((item >> 3) << 1) + (item & 1)) * 4;
;     const int ntile = (t0 + 4 + 31) >> 5;
;     bf16x8 af[4];
;     const bf16_t* iqp = proj + (size_t)(b * SEQ + t0 + ru) * EIN + C_IQ + rhead * 64 + hh * 8;
; #pragma unroll
;     for (int ks = 0; ks < 4; ++ks) af[ks] = ldg8(iqp + ks * 16);
;     float w[16];
; #pragma unroll
;     for (int i = 0; i < 16; ++i) {
;       const int uq = 2 * hh + (i >> 3), hd = (i & 3) + 4 * ((i >> 2) & 1);
;       w[i] = bf2f(proj[(size_t)(b * SEQ + t0 + uq) * EIN + C_IW + hd]) * 0.04419417382415922f;
;     }
; #pragma unroll 1
;     for (int kt0 = wave * 4; kt0 < ntile; kt0 += 32) {
;       bf16x8 kf[4][4];
;       const unsigned ko = (unsigned)((b * SEQ + kt0 * 32 + l31) * EIN + C_IK + hh * 8);
; #pragma unroll
;       for (int u = 0; u < 4; ++u)
; #pragma unroll
;         for (int ks = 0; ks < 4; ++ks) kf[u][ks] = ldg8(proj + ko + (unsigned)(u * 32 * EIN + ks * 16));
; #pragma unroll
;       for (int u = 0; u < 4; ++u) {
;         f32x16 acc = zero16();
; #pragma unroll
;         for (int ks = 0; ks < 4; ++ks) acc = MFMA32(af[ks], kf[u][ks], acc);
;         float s0 = 0.f, s1 = 0.f;
; #pragma unroll
;         for (int i = 0; i < 8; ++i) { s0 += w[i] * fmaxf(acc[i], 0.f); s1 += w[8 + i] * fmaxf(acc[8 + i], 0.f); }
;         const int key = (kt0 + u) * 32 + l31;
;         s0 += 0.f; s1 += 0.f;
;         sc[(2 * hh) * 8192 + key] = s0;
;         sc[(2 * hh + 1) * 8192 + key] = s1;
;         if (key <= t0 + 2 * hh) atomicAdd(hist + (2 * hh) * 256 + (fkey(s0) >> 24), 1u);
;         if (key <= t0 + 2 * hh + 1) atomicAdd(hist + (2 * hh + 1) * 256 + (fkey(s1) >> 24), 1u);
.LBB0_852:
	s_lshl_b32 s2, s35, 2
	s_and_b32 s2, s2, 4
	s_and_b32 s18, s35, -8
	s_or_b32 s24, s2, s18
	s_add_i32 s2, s24, 35
	s_lshl_b32 s18, s35, 12
	s_and_b32 s18, s18, 0x6000
	s_ashr_i32 s26, s2, 5
	s_add_i32 s25, s24, s18
	v_cmp_gt_i32_e32 vcc, s26, v98
	s_and_saveexec_b64 s[18:19], vcc
	s_cbranch_execz .LBB0_871
	v_or_b32_e32 v0, s25, v97
	v_mov_b64_e32 v[6:7], s[84:85]
	s_waitcnt lgkmcnt(0)
	v_mad_i64_i32 v[2:3], s[20:21], v0, s87, v[6:7]
	v_add_co_u32_e32 v2, vcc, 0x1000, v2
	v_or_b32_e32 v0, 1, v0
	s_nop 0
	v_addc_co_u32_e32 v3, vcc, 0, v3, vcc
	v_mad_i64_i32 v[6:7], s[20:21], v0, s87, v[6:7]
	s_movk_i32 s2, 0x1000
	v_add_co_u32_e32 v6, vcc, s2, v6
	v_or_b32_e32 v0, s25, v96
	s_nop 0
	v_addc_co_u32_e32 v7, vcc, 0, v7, vcc
	v_mad_i64_i32 v[10:11], s[20:21], v0, s87, v[92:93]
	flat_load_dwordx4 v[2:5], v[2:3] offset:944
	s_and_b32 s2, s88, 0x6000
	flat_load_dwordx4 v[6:9], v[6:7] offset:944
	s_nop 0
	flat_load_dwordx4 v[18:21], v[10:11] offset:3888
	flat_load_dwordx4 v[22:25], v[10:11] offset:3920
	flat_load_dwordx4 v[26:29], v[10:11] offset:3952
	flat_load_dwordx4 v[30:33], v[10:11] offset:3984
	v_add_u32_e32 v0, s2, v119
	v_lshrrev_b32_e32 v10, 5, v0
	v_lshlrev_b32_e32 v10, 11, v10
	v_and_b32_e32 v11, 31, v0
	v_lshl_or_b32 v10, v11, 4, v10
	v_add_u32_e32 v10, v10, v94
	v_add_u32_e32 v10, 0x8fff668, v10
	v_or_b32_e32 v120, s24, v97
	v_mov_b32_e32 v0, v10
	s_mov_b64 s[20:21], 0
	v_mov_b32_e32 v121, v119
	v_mov_b32_e32 v122, v118
	v_or_b32_e32 v123, 1, v120
	v_mov_b32_e32 v140, v98
	s_waitcnt vmcnt(0) lgkmcnt(0)
	v_lshlrev_b32_e32 v10, 16, v2
	v_and_b32_e32 v2, 0xffff0000, v2
	v_lshlrev_b32_e32 v11, 16, v3
	v_and_b32_e32 v3, 0xffff0000, v3
	v_lshlrev_b32_e32 v12, 16, v4
	v_and_b32_e32 v4, 0xffff0000, v4
	v_lshlrev_b32_e32 v13, 16, v5
	v_and_b32_e32 v5, 0xffff0000, v5
	v_lshlrev_b32_e32 v14, 16, v6
	v_and_b32_e32 v6, 0xffff0000, v6
	v_lshlrev_b32_e32 v15, 16, v7
	v_and_b32_e32 v7, 0xffff0000, v7
	v_lshlrev_b32_e32 v16, 16, v8
	v_and_b32_e32 v8, 0xffff0000, v8
	v_lshlrev_b32_e32 v17, 16, v9
	v_and_b32_e32 v9, 0xffff0000, v9
	v_mul_f32_e32 v124, 0x3d3504f3, v10
	v_mul_f32_e32 v125, 0x3d3504f3, v2
	v_mul_f32_e32 v126, 0x3d3504f3, v11
	v_mul_f32_e32 v127, 0x3d3504f3, v3
	v_mul_f32_e32 v128, 0x3d3504f3, v12
	v_mul_f32_e32 v129, 0x3d3504f3, v4
	v_mul_f32_e32 v130, 0x3d3504f3, v13
	v_mul_f32_e32 v131, 0x3d3504f3, v5
	v_mul_f32_e32 v132, 0x3d3504f3, v14
	v_mul_f32_e32 v133, 0x3d3504f3, v6
	v_mul_f32_e32 v134, 0x3d3504f3, v15
	v_mul_f32_e32 v135, 0x3d3504f3, v7
	v_mul_f32_e32 v136, 0x3d3504f3, v16
	v_mul_f32_e32 v137, 0x3d3504f3, v8
	v_mul_f32_e32 v138, 0x3d3504f3, v17
	v_mul_f32_e32 v139, 0x3d3504f3, v9
	s_branch .LBB0_855
.LBB0_854:
	s_or_b64 exec, exec, s[22:23]
	v_add_u32_e32 v140, 32, v140
	v_cmp_le_i32_e32 vcc, s26, v140
	v_add_u32_e32 v122, 0x1000, v122
	v_add_u32_e32 v121, 0x400, v121
	s_or_b64 s[20:21], vcc, s[20:21]
	v_add_u32_e32 v0, 0x10000, v0
	s_andn2_b64 exec, exec, s[20:21]
	s_cbranch_execz .LBB0_871
.LBB0_855:
	v_lshl_add_u64 v[38:39], v[0:1], 1, s[84:85]
	flat_load_dwordx4 v[2:5], v[38:39]
	flat_load_dwordx4 v[34:37], v[38:39] offset:1024
	flat_load_dwordx4 v[42:45], v[38:39] offset:2048
	flat_load_dwordx4 v[142:145], v[38:39] offset:3072
	v_add_co_u32_e32 v6, vcc, 0x1000, v38
	s_mov_b32 s2, 0x2000
	s_nop 0
	v_addc_co_u32_e32 v7, vcc, 0, v39, vcc
	flat_load_dwordx4 v[78:81], v[6:7]
	flat_load_dwordx4 v[74:77], v[6:7] offset:1024
	flat_load_dwordx4 v[70:73], v[6:7] offset:2048
	flat_load_dwordx4 v[66:69], v[6:7] offset:3072
	v_add_co_u32_e32 v40, vcc, s2, v38
	s_mov_b32 s2, 0x3000
	s_nop 0
	v_addc_co_u32_e32 v41, vcc, 0, v39, vcc
	v_add_co_u32_e32 v46, vcc, s2, v38
	flat_load_dwordx4 v[62:65], v[40:41]
	flat_load_dwordx4 v[54:57], v[40:41] offset:1024
	v_addc_co_u32_e32 v47, vcc, 0, v39, vcc
	flat_load_dwordx4 v[58:61], v[40:41] offset:2048
	flat_load_dwordx4 v[50:53], v[40:41] offset:3072
	v_cmp_le_i32_e32 vcc, v121, v120
	s_waitcnt vmcnt(0) lgkmcnt(0)
	v_mfma_f32_32x32x16_bf16 v[2:17], v[18:21], v[2:5], 0
	v_mfma_f32_32x32x16_bf16 v[2:17], v[22:25], v[34:37], v[2:17]
	flat_load_dwordx4 v[38:41], v[46:47]
	flat_load_dwordx4 v[34:37], v[46:47] offset:1024
	v_mfma_f32_32x32x16_bf16 v[2:17], v[26:29], v[42:45], v[2:17]
	flat_load_dwordx4 v[42:45], v[46:47] offset:2048
	s_nop 0
	flat_load_dwordx4 v[46:49], v[46:47] offset:3072
	v_mfma_f32_32x32x16_bf16 v[2:17], v[30:33], v[142:145], v[2:17]
	s_nop 11
	v_max_f32_e32 v2, v2, v2
	v_max_f32_e32 v10, v10, v10
	v_max_f32_e32 v3, v3, v3
	v_max_f32_e32 v11, v11, v11
	v_max_f32_e32 v2, 0, v2
	v_max_f32_e32 v10, 0, v10
	v_max_f32_e32 v4, v4, v4
	v_max_f32_e32 v12, v12, v12
	v_max_f32_e32 v3, 0, v3
	v_max_f32_e32 v11, 0, v11
	v_fma_f32 v2, v124, v2, 0
	v_fma_f32 v10, v132, v10, 0
	v_max_f32_e32 v5, v5, v5
	v_max_f32_e32 v13, v13, v13
	v_max_f32_e32 v4, 0, v4
	v_max_f32_e32 v12, 0, v12
	v_fmac_f32_e32 v2, v125, v3
	v_fmac_f32_e32 v10, v133, v11
	v_max_f32_e32 v6, v6, v6
	v_max_f32_e32 v14, v14, v14
	v_max_f32_e32 v5, 0, v5
	v_max_f32_e32 v13, 0, v13
	v_fmac_f32_e32 v2, v126, v4
	v_fmac_f32_e32 v10, v134, v12
	v_max_f32_e32 v7, v7, v7
	v_max_f32_e32 v15, v15, v15
	v_max_f32_e32 v6, 0, v6
	v_max_f32_e32 v14, 0, v14
	v_fmac_f32_e32 v2, v127, v5
	v_fmac_f32_e32 v10, v135, v13
	v_max_f32_e32 v8, v8, v8
	v_max_f32_e32 v16, v16, v16
	v_max_f32_e32 v7, 0, v7
	v_max_f32_e32 v15, 0, v15
	v_fmac_f32_e32 v2, v128, v6
	v_fmac_f32_e32 v10, v136, v14
	v_max_f32_e32 v9, v9, v9
	v_max_f32_e32 v17, v17, v17
	v_max_f32_e32 v8, 0, v8
	v_max_f32_e32 v16, 0, v16
	v_fmac_f32_e32 v2, v129, v7
	v_fmac_f32_e32 v10, v137, v15
	v_max_f32_e32 v9, 0, v9
	v_max_f32_e32 v17, 0, v17
	v_fmac_f32_e32 v2, v130, v8
	v_fmac_f32_e32 v10, v138, v16
	v_fmac_f32_e32 v2, v131, v9
	v_fmac_f32_e32 v10, v139, v17
	v_add_f32_e32 v3, 0, v2
	v_add_f32_e32 v2, 0, v10
	ds_write2st64_b32 v122, v3, v2 offset1:128
	s_and_saveexec_b64 s[22:23], vcc
	s_cbranch_execz .LBB0_857
	v_not_b32_e32 v4, v3
	v_or_b32_e32 v5, 0x80000000, v3
	v_cmp_gt_i32_e32 vcc, 0, v3
	s_nop 1
	v_cndmask_b32_e32 v3, v5, v4, vcc
	v_lshrrev_b32_e32 v3, 24, v3
	v_lshl_add_u32 v3, v3, 2, v99
	ds_add_u32 v3, v214
